# on top of v25: row-dependent 16-byte chunk-pair swizzle of the HGRN2 output-phase LDS tiles K^T, V^T, A and state (writers and fragment readers adjusted per lane) removes the 2-way bank conflicts of t
# speedup vs baseline: 1.0069x; 1.0058x over previous
; #define LAS __attribute__((address_space(3)))
; #define GAS __attribute__((address_space(1)))
; #define ARGP(i) ((const GAS float*)ldptr(ptab, (i)))
; __device__ __forceinline__ Ctx load_ctx(LAS unsigned long long* ptab) {
;     Ctx c; const int step = (int)ldptr(ptab, 16); c.NG = (int)ldptr(ptab, 15); c.layer = step / c.NG; c.g = step - c.layer * c.NG; c.TOKG = NTOK / c.NG; c.j = c.layer >> 1; c.even = !(c.layer & 1);
; __global__ void __launch_bounds__(512, 2) fwd(Args a) {
;     ...
;             const Ctx c = load_ctx(ptab);
;             if (__builtin_amdgcn_readfirstlane(c.tid) >= 256) __builtin_amdgcn_s_setprio(1);
;             if (c.even) merge_conv(c.proj, c.xn, (const GAS float*)(c.xn + (size_t)c.TOKG * 3072), c.ybuf, c.TOKG, ARGP(3) + c.j * 3 * 1024, c.lane, c.gw, c.ngw);
;             else hgrn_r3(c.proj, (const GAS float*)c.xn, (const GAS float*)(c.wsb + WS_RD), c.ybuf, c.TOKG, ARGP(11) + c.j * MW, lds, c.tid, c.lane, c.wave, c.bid, c.G);
.LBB0_374:
	s_abs_i32 s5, s4
	v_cvt_f32_u32_e32 v0, s5
	s_sub_i32 s8, 0, s5
	s_ashr_i32 s7, s3, 31
	s_abs_i32 s3, s3
	v_rcp_iflag_f32_e32 v0, v0
	s_ashr_i32 s4, s4, 31
	s_xor_b32 s7, s7, s4
	v_and_b32_e32 v99, 63, v98
	v_mul_f32_e32 v0, 0x4f7ffffe, v0
	v_cvt_u32_f32_e32 v0, v0
	s_nop 0
	v_readfirstlane_b32 s9, v0
	s_mul_i32 s8, s8, s9
	s_mul_hi_u32 s8, s9, s8
	s_add_i32 s9, s9, s8
	s_mul_hi_u32 s8, s3, s9
	s_mul_i32 s10, s8, s5
	s_sub_i32 s3, s3, s10
	s_add_i32 s11, s8, 1
	s_sub_i32 s10, s3, s5
	s_cmp_ge_u32 s3, s5
	s_cselect_b32 s8, s11, s8
	s_cselect_b32 s3, s10, s3
	s_add_i32 s10, s8, 1
	s_cmp_ge_u32 s3, s5
	s_cselect_b32 s3, s10, s8
	s_lshr_b32 s8, s9, 17
	s_xor_b32 s3, s3, s7
	s_mul_i32 s9, s8, s5
	s_sub_i32 s7, s3, s7
	s_sub_i32 s3, 0x8000, s9
	s_add_i32 s9, s8, 1
	s_sub_i32 s10, s3, s5
	s_cmp_ge_u32 s3, s5
	s_cselect_b32 s8, s9, s8
	s_cselect_b32 s3, s10, s3
	s_add_i32 s9, s8, 1
	s_cmp_ge_u32 s3, s5
	s_cselect_b32 s3, s9, s8
	s_xor_b32 s3, s3, s4
	s_sub_i32 s96, s3, s4
	s_ashr_i32 s97, s96, 31
	s_ashr_i32 s3, s7, 1
	s_ashr_i32 s40, s6, 6
	s_lshl_b64 s[98:99], s[96:97], 14
	s_bitcmp1_b32 s7, 0
	s_cselect_b64 s[8:9], -1, 0
	s_mov_b64 s[4:5], -1
	s_and_b64 vcc, exec, s[8:9]
	s_cbranch_vccz .LBB0_401
	v_readlane_b32 s4, v236, 30
	s_nop 1
	v_mov_b32_e32 v0, s4
	ds_read_b64 v[0:1], v0
	s_ashr_i32 s4, s96, 31
	s_lshr_b32 s4, s4, 19
	s_add_i32 s5, s96, s4
	s_ashr_i32 s5, s5, 13
	s_lshl_b32 s53, s5, 7
	s_waitcnt lgkmcnt(0)
	v_readfirstlane_b32 s4, v1
	s_cmp_ge_i32 s2, s53
	v_readfirstlane_b32 s5, v0
	s_cbranch_scc1 .LBB0_400
; #define GAS __attribute__((address_space(1)))
; __device__ __forceinline__ void hgrn_r3(const GAS bf16* proj, const GAS float* RU, const GAS float* RD, GAS bf16* y, int TOKG, const GAS float* ogain, unsigned char* lds, int tid, int lane, int wave, int bid, int G) {
;     ...
;     unsigned rq[8], rg[8], rv[8];
;     unsigned voff[8], zoff[4], yoff[4];
; #pragma unroll
;     for (int i = 0; i < 8; ++i) voff[i] = (unsigned)((wave * 8 + i) * (PW * 2) + lane * 4);
; #pragma unroll
;     for (int t2 = 0; t2 < 4; ++t2) { zoff[t2] = (unsigned)(((16 * t2 + fr) * PW + 16 * wave + 4 * fq) * 2); yoff[t2] = (unsigned)(((16 * t2 + fr) * MW + 16 * wave + 4 * fq) * 2); }
;     const __amdgpu_buffer_rsrc_t prs = __builtin_amdgcn_make_buffer_rsrc((void*)proj, 0, (int)((size_t)TOKG * PW * 2), 0x00020000);
;     ...
;     for (int run = bid; run < nruns; run += G) {
;         const int u0 = run * RUNC, seq = run / (128 / RUNC), rr = run - seq * (128 / RUNC), h = seq & 15, bl = seq >> 4;
;         H3_LOAD(u0);
;         const int v0 = 16 * wave + 4 * fq;
;         const f32x4 og = *(const GAS f32x4*)(ogain + h * 128 + v0);
	s_add_u32 s44, s0, 0x1800000
	s_addc_u32 s56, s1, 0
	s_lshl_b32 s46, s96, 14
	s_and_b32 s45, s56, 0xffff
	s_add_u32 s57, s44, s98
	s_addc_u32 s74, s56, s99
	s_lshl_b64 s[8:9], s[96:97], 12
	s_add_u32 s8, s57, s8
	s_addc_u32 s9, s74, s9
	s_lshl_b32 s10, s3, 11
	s_ashr_i32 s11, s10, 31
	s_lshl_b64 s[10:11], s[10:11], 2
	v_lshrrev_b32_e32 v2, 4, v99
	s_add_u32 s10, s5, s10
	v_lshlrev_b32_e32 v0, 2, v99
	v_lshlrev_b32_e32 v3, 2, v2
	s_addc_u32 s11, s4, s11
	s_lshl_b32 s75, s40, 4
	v_lshl_or_b32 v100, s40, 17, v0
	v_and_b32_e32 v4, 15, v98
	v_or_b32_e32 v0, s75, v3
	v_or_b32_e32 v1, 48, v4
	v_lshlrev_b32_e32 v5, 1, v0
	v_lshl_add_u32 v68, v1, 12, v5
	s_movk_i32 s4, 0x3000
	v_mad_u32_u24 v70, v1, s4, v68
	v_or_b32_e32 v1, 32, v4
	v_lshl_add_u32 v72, v1, 12, v5
	v_mad_u32_u24 v74, v1, s4, v72
	v_or_b32_e32 v1, 16, v4
	v_lshl_add_u32 v76, v1, 12, v5
	v_mad_u32_u24 v78, v1, s4, v76
	s_waitcnt vmcnt(0)
	v_lshl_add_u32 v80, v4, 12, v5
	v_ashrrev_i32_e32 v1, 31, v0
	v_or_b32_e32 v5, s75, v4
	v_lshl_add_u64 v[84:85], v[0:1], 2, s[10:11]
	v_lshlrev_b32_e32 v0, 7, v5
	v_mad_u32_u24 v82, v4, s4, v80
	s_lshl_b32 s4, s40, 2
	v_ashrrev_i32_e32 v1, 31, v0
	s_add_i32 s4, s4, 0
	v_lshl_add_u64 v[0:1], v[0:1], 2, s[8:9]
	v_and_b32_e32 v112, 48, v99
	s_add_i32 s42, s4, 0x14800
	v_lshl_add_u64 v[86:87], v[0:1], 0, v[112:113]
	v_lshl_add_u64 v[0:1], s[0:1], 0, v[112:113]
	s_mov_b64 s[4:5], 0x1410000
	s_movk_i32 s25, 0x110
	v_lshl_add_u64 v[88:89], v[0:1], 0, s[4:5]
	v_mul_lo_u32 v0, v5, s25
	v_readlane_b32 s4, v236, 31
	s_add_i32 s5, 0, 0x13800
	v_lshlrev_b32_e32 v1, 3, v99
	v_add_u32_e32 v108, s4, v0
	s_lshl_b32 s4, s40, 9
	s_add_i32 s4, s5, s4
	v_add_u32_e32 v116, s5, v1
	v_readlane_b32 s5, v236, 32
	s_movk_i32 s7, 0x120
	s_add_i32 s43, s5, s75
	v_add_u32_e32 v110, s4, v1
	v_mad_u32_u24 v111, v99, s7, 0
	s_movk_i32 s4, 0xfee4
	s_cmp_lt_u32 s6, 64
	v_mad_i32_i24 v6, v99, s4, v111
	s_cselect_b64 s[70:71], -1, 0
	s_ashr_i32 s22, s6, 7
	s_lshl_b32 s4, s40, 1
	v_mov_b32_e32 v7, s5
	s_and_b32 s23, s4, 2
	v_lshl_or_b32 v8, s22, 4, v4
	s_movk_i32 s4, 0x90
	v_and_b32_e32 v109, 48, v98
	v_mad_u32_u24 v7, v99, s7, v7
	v_mul_lo_u32 v9, v8, s4
	v_readlane_b32 s6, v236, 33
	v_readlane_b32 s7, v236, 34
	s_cmp_gt_i32 s40, 0
	v_add_u32_e32 v9, s6, v9
	v_add_u32_e32 v117, s7, v112
	v_add_u32_e32 v13, s6, v109
	v_add_u32_e32 v120, s7, v1
	s_cselect_b64 s[6:7], -1, 0
	s_cmp_gt_i32 s40, 1
	s_cselect_b64 s[8:9], -1, 0
	s_cmp_gt_i32 s40, 2
	s_cselect_b64 s[10:11], -1, 0
	s_cmp_gt_i32 s40, 3
	s_cselect_b64 s[12:13], -1, 0
	s_cmp_gt_i32 s40, 4
	s_cselect_b64 s[14:15], -1, 0
	s_cmp_gt_i32 s40, 5
	s_cselect_b64 s[16:17], -1, 0
	s_cmp_gt_i32 s40, 6
	v_and_b32_e32 v15, 64, v190
	s_cselect_b64 s[18:19], -1, 0
	s_cmp_gt_i32 s40, 7
	v_xor_b32_e32 v14, 16, v190
	v_add_u32_e32 v15, 64, v15
	s_cselect_b64 s[20:21], -1, 0
	s_cmp_le_i32 s23, s22
	v_cmp_lt_i32_e32 vcc, v14, v15
	s_cselect_b64 s[82:83], -1, 0
	s_lshl_b32 s24, s23, 4
	v_cndmask_b32_e32 v14, v190, v14, vcc
	s_cmp_lt_i32 s23, s22
	v_or_b32_e32 v18, s24, v3
	v_lshlrev_b32_e32 v118, 2, v14
	v_xor_b32_e32 v14, 32, v190
	s_cselect_b64 s[48:49], -1, 0
	s_or_b32 s30, s24, 16
	v_or_b32_e32 v19, 2, v18
	v_cmp_lt_i32_e32 vcc, v14, v15
	v_cmp_gt_i32_e64 s[26:27], v19, v8
	v_or_b32_e32 v19, 3, v18
	v_or_b32_e32 v3, s30, v3
	v_lshlrev_b32_e32 v0, 3, v2
	v_mul_lo_u32 v10, v8, s25
	v_mul_lo_u32 v5, v5, s4
	v_cndmask_b32_e32 v14, v190, v14, vcc
	v_lshlrev_b32_e32 v15, 5, v4
	v_or_b32_e32 v1, s24, v4
	v_or_b32_e32 v16, s30, v4
	v_cmp_gt_i32_e64 s[28:29], v19, v8
	v_or_b32_e32 v19, 2, v3
	v_mul_u32_u24_e32 v2, 0x120, v99
	v_add_u32_e32 v10, 0, v10
	v_add_u32_e32 v11, 0, v109
	v_add_u32_e32 v5, 0, v5
	v_add_u32_e32 v12, s5, v109
	v_lshlrev_b32_e32 v119, 2, v14
	v_lshlrev_b32_e32 v14, 5, v99
	s_mul_i32 s54, s40, 0x880
	v_mad_u32_u24 v1, v1, s25, 0
	v_mad_u32_u24 v16, v16, s25, 0
	v_mul_u32_u24_e32 v17, 0x110, v4
	v_mul_u32_u24_e32 v4, 0x90, v4
	v_cmp_gt_i32_e64 s[22:23], v18, v8
	v_cmp_lt_i32_e64 s[24:25], v18, v8
	v_lshlrev_b32_e32 v18, 1, v18
	v_cmp_gt_i32_e64 s[30:31], v3, v8
	v_cmp_lt_i32_e64 s[34:35], v3, v8
	v_cmp_gt_i32_e64 s[36:37], v19, v8
	v_or_b32_e32 v19, 3, v3
	v_lshlrev_b32_e32 v3, 1, v3
	v_add_u32_e32 v121, v108, v0
	v_add_u32_e32 v0, 0, v15
	v_or_b32_e32 v101, 0x4000, v100
	v_or_b32_e32 v102, 0x8000, v100
	v_or_b32_e32 v103, 0xc000, v100
	v_or_b32_e32 v104, 0x10000, v100
	v_or_b32_e32 v105, 0x14000, v100
	v_or_b32_e32 v106, 0x18000, v100
	v_or_b32_e32 v107, 0x1c000, v100
	v_cmp_gt_u32_e64 s[4:5], 16, v99
	v_mov_b32_e32 v83, v113
	v_mov_b32_e32 v79, v113
	v_mov_b32_e32 v75, v113
	v_mov_b32_e32 v71, v113
	v_mov_b32_e32 v81, v113
	v_mov_b32_e32 v77, v113
	v_mov_b32_e32 v73, v113
	v_mov_b32_e32 v69, v113
	v_cmp_gt_i32_e64 s[38:39], v19, v8
	v_add_u32_e32 v122, s54, v6
	v_add_u32_e32 v123, s75, v7
	v_add_u32_e32 v124, s43, v2
	v_add_u32_e32 v125, v1, v109
	v_add_u32_e32 v126, v9, v18
	v_add_u32_e32 v127, v16, v109
	v_add_u32_e32 v128, v9, v3
	v_add_u32_e32 v129, v11, v17
	v_add_u32_e32 v130, v5, v109
	v_add_u32_e32 v131, v12, v4
	v_add_u32_e32 v132, v13, v4
	v_add_u32_e32 v133, 0x14800, v0
	v_add_u32_e32 v134, v10, v109
	v_add_u32_e32 v135, s42, v14
	v_add_u32_e32 v213, 4, v99
	v_and_b32_e32 v213, 8, v213
	v_lshlrev_b32_e32 v213, 1, v213
	v_lshrrev_b32_e32 v234, 1, v99
	v_and_b32_e32 v234, 16, v234
	v_xor_b32_e32 v235, v234, v213
	v_sub_u32_e32 v235, v235, v234
	v_add_u32_e32 v126, v126, v235
	v_add_u32_e32 v128, v128, v235
	v_add_u32_e32 v121, v121, v235
	v_and_b32_e32 v234, 16, v99
	v_xor_b32_e32 v235, v234, v213
	v_sub_u32_e32 v213, v235, v234
	v_add_u32_e32 v130, v130, v213
	v_add_u32_e32 v131, v131, v213
	v_add_u32_e32 v132, v132, v213
	v_lshlrev_b32_e32 v234, 1, v99
	v_add_u32_e32 v234, 4, v234
	v_and_b32_e32 v234, 8, v234
	v_lshlrev_b32_e32 v234, 1, v234
	v_mov_b32_e32 v235, s75
	v_and_b32_e32 v235, 16, v235
	v_xor_b32_e32 v234, v234, v235
	v_sub_u32_e32 v234, v234, v235
	v_add_u32_e32 v123, v123, v234
	v_add_u32_e32 v124, v124, v234
	v_add_u32_e32 v111, v111, v234
	v_readlane_b32 s76, v236, 18
	v_readlane_b32 s68, v236, 17
	v_readlane_b32 s87, v236, 16
	v_readlane_b32 s94, v236, 15
	s_mov_b32 s97, s2
	s_branch .LBB0_378

; #define LAS __attribute__((address_space(3)))
; #define GAS __attribute__((address_space(1)))
; __device__ __forceinline__ unsigned pkbf(float lo, float hi) { const f32x2_t v = {lo, hi}; const bf16x2_t b = __builtin_convertvector(v, bf16x2_t); return __builtin_bit_cast(unsigned, b); }
; __device__ __forceinline__ void hgrn_r3(const GAS bf16* proj, const GAS float* RU, const GAS float* RD, GAS bf16* y, int TOKG, const GAS float* ogain, unsigned char* lds, int tid, int lane, int wave, int bid, int G) {
;     ...
;             const int u = u0 + ci, cch = u & 127;
;             const size_t rowc = (size_t)bl * SEQ + cch * 64;
;             v2u zw[4];
;             { const GAS char* zb = (const GAS char*)(proj + rowc * PW + 6144 + h * 128);
; #pragma unroll
;               for (int t2 = 0; t2 < 4; ++t2) zw[t2] = *(const GAS v2u*)(zb + zoff[t2]); }
;             bf16x8 sf[4];
;             { LAS unsigned char* sl = L + H3_SL + (16 * wave + fr) * HQS;
; #pragma unroll
;               for (int nk = 0; nk < 8; ++nk) { v2u w; w.x = pkbf(Sm[nk][0], Sm[nk][1]); w.y = pkbf(Sm[nk][2], Sm[nk][3]); *(LAS v2u*)(sl + (16 * nk + 4 * fq) * 2) = w; }
; #pragma unroll
;               for (int ks = 0; ks < 4; ++ks) sf[ks] = *(const LAS bf16x8*)(sl + (32 * ks + 8 * fq) * 2); }
.LBB0_384:
	s_and_b32 s42, s81, 0x1fc0
	s_or_b32 s42, s54, s42
	s_mov_b32 s43, s55
	s_lshl_b64 vcc, s[42:43], 14
	s_add_u32 s64, s44, vcc_lo
	s_addc_u32 s65, s56, vcc_hi
	s_add_u32 s64, s64, s60
	s_addc_u32 s65, s65, 0
	s_add_u32 vcc_lo, s64, 0x3000
	s_addc_u32 vcc_hi, s65, 0
	v_lshl_add_u64 v[36:37], vcc, 0, v[82:83]
	v_lshl_add_u64 v[38:39], vcc, 0, v[78:79]
	v_lshl_add_u64 v[40:41], vcc, 0, v[74:75]
	v_lshl_add_u64 v[42:43], vcc, 0, v[70:71]
	global_load_dwordx2 v[96:97], v[36:37], off
	global_load_dwordx2 v[94:95], v[38:39], off
	global_load_dwordx2 v[92:93], v[40:41], off
	global_load_dwordx2 v[90:91], v[42:43], off
	v_cvt_pk_bf16_f32 v36, v20, v21
	v_cvt_pk_bf16_f32 v37, v22, v23
	v_cvt_pk_bf16_f32 v38, v4, v5
	v_cvt_pk_bf16_f32 v39, v6, v7
	ds_write2_b64 v121, v[36:37], v[38:39] offset1:4
	v_cvt_pk_bf16_f32 v36, v16, v17
	v_cvt_pk_bf16_f32 v37, v18, v19
	v_cvt_pk_bf16_f32 v38, v8, v9
	v_cvt_pk_bf16_f32 v39, v10, v11
	ds_write2_b64 v121, v[36:37], v[38:39] offset0:8 offset1:12
	v_cvt_pk_bf16_f32 v36, v24, v25
	v_cvt_pk_bf16_f32 v37, v26, v27
	v_cvt_pk_bf16_f32 v38, v12, v13
	v_cvt_pk_bf16_f32 v39, v14, v15
	ds_write2_b64 v121, v[36:37], v[38:39] offset0:16 offset1:20
	v_cvt_pk_bf16_f32 v36, v28, v29
	v_cvt_pk_bf16_f32 v37, v30, v31
	v_cvt_pk_bf16_f32 v38, v32, v33
	v_cvt_pk_bf16_f32 v39, v34, v35
	ds_write2_b64 v121, v[36:37], v[38:39] offset0:24 offset1:28
	v_add_u32_e32 v36, v108, v109
	v_add_u32_e32 v36, v36, v213
	ds_read_b128 v[48:51], v36
	ds_read_b128 v[44:47], v36 offset:64
	ds_read_b128 v[40:43], v36 offset:128
	ds_read_b128 v[36:39], v36 offset:192
	s_cmp_eq_u32 s80, 15
	s_cbranch_scc1 .LBB0_386
	s_add_i32 s64, s94, s80
	s_and_b32 s65, s77, 0x3f80000
	s_and_b32 s64, s64, 0x780
	s_and_b32 vcc_lo, s69, 0x7c000000
	s_or_b32 s64, s65, s64
	s_or_b32 s64, s64, vcc_lo
	s_lshl_b32 s64, s64, 1
	s_or_b32 s65, s64, 0x1000
	s_or_b32 vcc_lo, s64, 0x2000
	buffer_load_dword v139, v100, s[44:47], s64 offen
	buffer_load_dword v115, v100, s[44:47], s65 offen
	buffer_load_dword v112, v100, s[44:47], vcc_lo offen
	buffer_load_dword v142, v101, s[44:47], s64 offen
	buffer_load_dword v137, v101, s[44:47], s65 offen
	buffer_load_dword v114, v101, s[44:47], vcc_lo offen
	buffer_load_dword v145, v102, s[44:47], s64 offen
	buffer_load_dword v140, v102, s[44:47], s65 offen
	buffer_load_dword v136, v102, s[44:47], vcc_lo offen
	buffer_load_dword v148, v103, s[44:47], s64 offen
	buffer_load_dword v143, v103, s[44:47], s65 offen
	buffer_load_dword v138, v103, s[44:47], vcc_lo offen
	buffer_load_dword v151, v104, s[44:47], s64 offen
	buffer_load_dword v146, v104, s[44:47], s65 offen
	buffer_load_dword v141, v104, s[44:47], vcc_lo offen
	buffer_load_dword v153, v105, s[44:47], s64 offen
	buffer_load_dword v149, v105, s[44:47], s65 offen
	buffer_load_dword v144, v105, s[44:47], vcc_lo offen
	buffer_load_dword v155, v106, s[44:47], s64 offen
	buffer_load_dword v152, v106, s[44:47], s65 offen
	buffer_load_dword v147, v106, s[44:47], vcc_lo offen
	buffer_load_dword v156, v107, s[44:47], s64 offen
	buffer_load_dword v154, v107, s[44:47], s65 offen
	buffer_load_dword v150, v107, s[44:47], vcc_lo offen
